# P8 final rmsnorm row loop hand-scheduled: gain vector held in registers, all 8 row loads issued together, two rows in flight
# speedup vs baseline: 1.0048x; 1.0048x over previous
; #define KIN(i) (*(const float* const __attribute__((address_space(4)))*)(kp + 8 * (i)))
; __global__ void __launch_bounds__(NTHREADS, 2) fwd_megakernel(Args args) {
;     ...
;         const float* ss3 = SS + 3 * T; const f32x4* gf = (const f32x4*)KIN(19);
;         f32x4* X4 = (f32x4*)X;
;         for (int row = gw; row < T; row += NGW) {
;             f32x4* xr = X4 + (size_t)row * (D / 4) + lane;
;             const float r = __builtin_amdgcn_rsqf(ss3[row] * (1.0f / D) + EPS);
;             f32x4 v[8];
; #pragma unroll
;             for (int j = 0; j < 8; ++j) v[j] = xr[64 * j];
; #pragma unroll
;             for (int j = 0; j < 8; ++j) xr[64 * j] = v[j] * r * gf[lane + 64 * j];
;         }
.LBB0_1505:
	global_load_dwordx4 v[32:35], v[2:3], off
	global_load_dwordx4 v[36:39], v[2:3], off offset:1024
	global_load_dwordx4 v[40:43], v[2:3], off offset:2048
	global_load_dwordx4 v[44:47], v[2:3], off offset:3072
	global_load_dwordx4 v[48:51], v[4:5], off
	global_load_dwordx4 v[52:55], v[6:7], off
	global_load_dwordx4 v[56:59], v[8:9], off
	global_load_dwordx4 v[60:63], v[10:11], off
	v_add_co_u32_e32 v14, vcc, 0xfffff400, v12
	s_nop 1
	v_addc_co_u32_e32 v15, vcc, -1, v13, vcc
	global_load_dword v28, v1, s[0:1]
	s_add_u32 s0, s0, s2
	s_addc_u32 s1, s1, s3
	global_load_dwordx4 v[64:67], v[14:15], off offset:-4096
	global_load_dwordx4 v[68:71], v[14:15], off offset:-3072
	global_load_dwordx4 v[72:75], v[14:15], off offset:-2048
	global_load_dwordx4 v[76:79], v[14:15], off offset:-1024
	global_load_dwordx4 v[80:83], v[14:15], off offset:0
	global_load_dwordx4 v[84:87], v[14:15], off offset:1024
	global_load_dwordx4 v[88:91], v[14:15], off offset:2048
	global_load_dwordx4 v[92:95], v[14:15], off offset:3072
	s_add_i32 s6, s6, s24
	s_cmpk_gt_i32 s6, 0x47ff
	s_cbranch_scc1 .Lp8_tail_a
	v_lshl_add_u64 v[16:17], v[14:15], 0, s[4:5]
	global_load_dword v30, v1, s[0:1]
	s_add_u32 s0, s0, s2
	s_addc_u32 s1, s1, s3
	global_load_dwordx4 v[96:99], v[16:17], off offset:-4096
	global_load_dwordx4 v[100:103], v[16:17], off offset:-3072
	global_load_dwordx4 v[104:107], v[16:17], off offset:-2048
	global_load_dwordx4 v[108:111], v[16:17], off offset:-1024
	global_load_dwordx4 v[112:115], v[16:17], off offset:0
	global_load_dwordx4 v[116:119], v[16:17], off offset:1024
	global_load_dwordx4 v[120:123], v[16:17], off offset:2048
	global_load_dwordx4 v[124:127], v[16:17], off offset:3072
	s_waitcnt vmcnt(9)
	v_fmamk_f32 v28, v28, 0x3a000000, v0
	v_rsq_f32_e32 v28, v28
	s_nop 0
	v_mul_f32_e32 v64, v28, v64
	v_mul_f32_e32 v65, v28, v65
	v_mul_f32_e32 v66, v28, v66
	v_mul_f32_e32 v67, v28, v67
	v_mul_f32_e32 v64, v64, v32
	v_mul_f32_e32 v65, v65, v33
	v_mul_f32_e32 v66, v66, v34
	v_mul_f32_e32 v67, v67, v35
	global_store_dwordx4 v[14:15], v[64:67], off offset:-4096
	v_mul_f32_e32 v68, v28, v68
	v_mul_f32_e32 v69, v28, v69
	v_mul_f32_e32 v70, v28, v70
	v_mul_f32_e32 v71, v28, v71
	v_mul_f32_e32 v68, v68, v36
	v_mul_f32_e32 v69, v69, v37
	v_mul_f32_e32 v70, v70, v38
	v_mul_f32_e32 v71, v71, v39
	global_store_dwordx4 v[14:15], v[68:71], off offset:-3072
	v_mul_f32_e32 v72, v28, v72
	v_mul_f32_e32 v73, v28, v73
	v_mul_f32_e32 v74, v28, v74
	v_mul_f32_e32 v75, v28, v75
	v_mul_f32_e32 v72, v72, v40
	v_mul_f32_e32 v73, v73, v41
	v_mul_f32_e32 v74, v74, v42
	v_mul_f32_e32 v75, v75, v43
	global_store_dwordx4 v[14:15], v[72:75], off offset:-2048
	v_mul_f32_e32 v76, v28, v76
	v_mul_f32_e32 v77, v28, v77
	v_mul_f32_e32 v78, v28, v78
	v_mul_f32_e32 v79, v28, v79
	v_mul_f32_e32 v76, v76, v44
	v_mul_f32_e32 v77, v77, v45
	v_mul_f32_e32 v78, v78, v46
	v_mul_f32_e32 v79, v79, v47
	global_store_dwordx4 v[14:15], v[76:79], off offset:-1024
	v_mul_f32_e32 v80, v28, v80
	v_mul_f32_e32 v81, v28, v81
	v_mul_f32_e32 v82, v28, v82
	v_mul_f32_e32 v83, v28, v83
	v_mul_f32_e32 v80, v80, v48
	v_mul_f32_e32 v81, v81, v49
	v_mul_f32_e32 v82, v82, v50
	v_mul_f32_e32 v83, v83, v51
	global_store_dwordx4 v[14:15], v[80:83], off offset:0
	v_mul_f32_e32 v84, v28, v84
	v_mul_f32_e32 v85, v28, v85
	v_mul_f32_e32 v86, v28, v86
	v_mul_f32_e32 v87, v28, v87
	v_mul_f32_e32 v84, v84, v52
	v_mul_f32_e32 v85, v85, v53
	v_mul_f32_e32 v86, v86, v54
	v_mul_f32_e32 v87, v87, v55
	global_store_dwordx4 v[14:15], v[84:87], off offset:1024
	v_mul_f32_e32 v88, v28, v88
	v_mul_f32_e32 v89, v28, v89
	v_mul_f32_e32 v90, v28, v90
	v_mul_f32_e32 v91, v28, v91
	v_mul_f32_e32 v88, v88, v56
	v_mul_f32_e32 v89, v89, v57
	v_mul_f32_e32 v90, v90, v58
	v_mul_f32_e32 v91, v91, v59
	global_store_dwordx4 v[14:15], v[88:91], off offset:2048
	v_mul_f32_e32 v92, v28, v92
	v_mul_f32_e32 v93, v28, v93
	v_mul_f32_e32 v94, v28, v94
	v_mul_f32_e32 v95, v28, v95
	v_mul_f32_e32 v92, v92, v60
	v_mul_f32_e32 v93, v93, v61
	v_mul_f32_e32 v94, v94, v62
	v_mul_f32_e32 v95, v95, v63
	global_store_dwordx4 v[14:15], v[92:95], off offset:3072
.Lp8_loop:
	s_add_i32 s6, s6, s24
	s_cmpk_gt_i32 s6, 0x47ff
	s_cbranch_scc1 .Lp8_tail_b
	v_lshl_add_u64 v[14:15], v[16:17], 0, s[4:5]
	global_load_dword v28, v1, s[0:1]
	s_add_u32 s0, s0, s2
	s_addc_u32 s1, s1, s3
	global_load_dwordx4 v[64:67], v[14:15], off offset:-4096
	global_load_dwordx4 v[68:71], v[14:15], off offset:-3072
	global_load_dwordx4 v[72:75], v[14:15], off offset:-2048
	global_load_dwordx4 v[76:79], v[14:15], off offset:-1024
	global_load_dwordx4 v[80:83], v[14:15], off offset:0
	global_load_dwordx4 v[84:87], v[14:15], off offset:1024
	global_load_dwordx4 v[88:91], v[14:15], off offset:2048
	global_load_dwordx4 v[92:95], v[14:15], off offset:3072
	s_waitcnt vmcnt(17)
; #define KIN(i) (*(const float* const __attribute__((address_space(4)))*)(kp + 8 * (i)))
; __global__ void __launch_bounds__(NTHREADS, 2) fwd_megakernel(Args args) {
;     ...
;         const float* ss3 = SS + 3 * T; const f32x4* gf = (const f32x4*)KIN(19);
;         f32x4* X4 = (f32x4*)X;
;         for (int row = gw; row < T; row += NGW) {
;             f32x4* xr = X4 + (size_t)row * (D / 4) + lane;
;             const float r = __builtin_amdgcn_rsqf(ss3[row] * (1.0f / D) + EPS);
;             f32x4 v[8];
; #pragma unroll
;             for (int j = 0; j < 8; ++j) v[j] = xr[64 * j];
; #pragma unroll
;             for (int j = 0; j < 8; ++j) xr[64 * j] = v[j] * r * gf[lane + 64 * j];
;         }
	v_fmamk_f32 v30, v30, 0x3a000000, v0
	v_rsq_f32_e32 v30, v30
	s_nop 0
	v_mul_f32_e32 v96, v30, v96
	v_mul_f32_e32 v97, v30, v97
	v_mul_f32_e32 v98, v30, v98
	v_mul_f32_e32 v99, v30, v99
	v_mul_f32_e32 v96, v96, v32
	v_mul_f32_e32 v97, v97, v33
	v_mul_f32_e32 v98, v98, v34
	v_mul_f32_e32 v99, v99, v35
	global_store_dwordx4 v[16:17], v[96:99], off offset:-4096
	v_mul_f32_e32 v100, v30, v100
	v_mul_f32_e32 v101, v30, v101
	v_mul_f32_e32 v102, v30, v102
	v_mul_f32_e32 v103, v30, v103
	v_mul_f32_e32 v100, v100, v36
	v_mul_f32_e32 v101, v101, v37
	v_mul_f32_e32 v102, v102, v38
	v_mul_f32_e32 v103, v103, v39
	global_store_dwordx4 v[16:17], v[100:103], off offset:-3072
	v_mul_f32_e32 v104, v30, v104
	v_mul_f32_e32 v105, v30, v105
	v_mul_f32_e32 v106, v30, v106
	v_mul_f32_e32 v107, v30, v107
	v_mul_f32_e32 v104, v104, v40
	v_mul_f32_e32 v105, v105, v41
	v_mul_f32_e32 v106, v106, v42
	v_mul_f32_e32 v107, v107, v43
	global_store_dwordx4 v[16:17], v[104:107], off offset:-2048
	v_mul_f32_e32 v108, v30, v108
	v_mul_f32_e32 v109, v30, v109
	v_mul_f32_e32 v110, v30, v110
	v_mul_f32_e32 v111, v30, v111
	v_mul_f32_e32 v108, v108, v44
	v_mul_f32_e32 v109, v109, v45
	v_mul_f32_e32 v110, v110, v46
	v_mul_f32_e32 v111, v111, v47
	global_store_dwordx4 v[16:17], v[108:111], off offset:-1024
	v_mul_f32_e32 v112, v30, v112
	v_mul_f32_e32 v113, v30, v113
	v_mul_f32_e32 v114, v30, v114
	v_mul_f32_e32 v115, v30, v115
	v_mul_f32_e32 v112, v112, v48
	v_mul_f32_e32 v113, v113, v49
	v_mul_f32_e32 v114, v114, v50
	v_mul_f32_e32 v115, v115, v51
	global_store_dwordx4 v[16:17], v[112:115], off offset:0
	v_mul_f32_e32 v116, v30, v116
	v_mul_f32_e32 v117, v30, v117
	v_mul_f32_e32 v118, v30, v118
	v_mul_f32_e32 v119, v30, v119
	v_mul_f32_e32 v116, v116, v52
	v_mul_f32_e32 v117, v117, v53
	v_mul_f32_e32 v118, v118, v54
	v_mul_f32_e32 v119, v119, v55
	global_store_dwordx4 v[16:17], v[116:119], off offset:1024
	v_mul_f32_e32 v120, v30, v120
	v_mul_f32_e32 v121, v30, v121
	v_mul_f32_e32 v122, v30, v122
	v_mul_f32_e32 v123, v30, v123
	v_mul_f32_e32 v120, v120, v56
	v_mul_f32_e32 v121, v121, v57
	v_mul_f32_e32 v122, v122, v58
	v_mul_f32_e32 v123, v123, v59
	global_store_dwordx4 v[16:17], v[120:123], off offset:2048
	v_mul_f32_e32 v124, v30, v124
	v_mul_f32_e32 v125, v30, v125
	v_mul_f32_e32 v126, v30, v126
	v_mul_f32_e32 v127, v30, v127
	v_mul_f32_e32 v124, v124, v60
	v_mul_f32_e32 v125, v125, v61
	v_mul_f32_e32 v126, v126, v62
	v_mul_f32_e32 v127, v127, v63
	global_store_dwordx4 v[16:17], v[124:127], off offset:3072
	s_add_i32 s6, s6, s24
	s_cmpk_gt_i32 s6, 0x47ff
	s_cbranch_scc1 .Lp8_tail_a
	v_lshl_add_u64 v[16:17], v[14:15], 0, s[4:5]
	global_load_dword v30, v1, s[0:1]
	s_add_u32 s0, s0, s2
	s_addc_u32 s1, s1, s3
	global_load_dwordx4 v[96:99], v[16:17], off offset:-4096
	global_load_dwordx4 v[100:103], v[16:17], off offset:-3072
	global_load_dwordx4 v[104:107], v[16:17], off offset:-2048
	global_load_dwordx4 v[108:111], v[16:17], off offset:-1024
	global_load_dwordx4 v[112:115], v[16:17], off offset:0
	global_load_dwordx4 v[116:119], v[16:17], off offset:1024
	global_load_dwordx4 v[120:123], v[16:17], off offset:2048
	global_load_dwordx4 v[124:127], v[16:17], off offset:3072
	s_waitcnt vmcnt(17)
	v_fmamk_f32 v28, v28, 0x3a000000, v0
	v_rsq_f32_e32 v28, v28
	s_nop 0
	v_mul_f32_e32 v64, v28, v64
	v_mul_f32_e32 v65, v28, v65
	v_mul_f32_e32 v66, v28, v66
	v_mul_f32_e32 v67, v28, v67
	v_mul_f32_e32 v64, v64, v32
	v_mul_f32_e32 v65, v65, v33
	v_mul_f32_e32 v66, v66, v34
	v_mul_f32_e32 v67, v67, v35
	global_store_dwordx4 v[14:15], v[64:67], off offset:-4096
	v_mul_f32_e32 v68, v28, v68
	v_mul_f32_e32 v69, v28, v69
	v_mul_f32_e32 v70, v28, v70
	v_mul_f32_e32 v71, v28, v71
	v_mul_f32_e32 v68, v68, v36
	v_mul_f32_e32 v69, v69, v37
	v_mul_f32_e32 v70, v70, v38
	v_mul_f32_e32 v71, v71, v39
	global_store_dwordx4 v[14:15], v[68:71], off offset:-3072
	v_mul_f32_e32 v72, v28, v72
	v_mul_f32_e32 v73, v28, v73
	v_mul_f32_e32 v74, v28, v74
	v_mul_f32_e32 v75, v28, v75
	v_mul_f32_e32 v72, v72, v40
	v_mul_f32_e32 v73, v73, v41
	v_mul_f32_e32 v74, v74, v42
	v_mul_f32_e32 v75, v75, v43
	global_store_dwordx4 v[14:15], v[72:75], off offset:-2048
	v_mul_f32_e32 v76, v28, v76
	v_mul_f32_e32 v77, v28, v77
	v_mul_f32_e32 v78, v28, v78
	v_mul_f32_e32 v79, v28, v79
	v_mul_f32_e32 v76, v76, v44
	v_mul_f32_e32 v77, v77, v45
	v_mul_f32_e32 v78, v78, v46
	v_mul_f32_e32 v79, v79, v47
	global_store_dwordx4 v[14:15], v[76:79], off offset:-1024
	v_mul_f32_e32 v80, v28, v80
	v_mul_f32_e32 v81, v28, v81
	v_mul_f32_e32 v82, v28, v82
	v_mul_f32_e32 v83, v28, v83
	v_mul_f32_e32 v80, v80, v48
	v_mul_f32_e32 v81, v81, v49
	v_mul_f32_e32 v82, v82, v50
	v_mul_f32_e32 v83, v83, v51
	global_store_dwordx4 v[14:15], v[80:83], off offset:0
	v_mul_f32_e32 v84, v28, v84
	v_mul_f32_e32 v85, v28, v85
	v_mul_f32_e32 v86, v28, v86
	v_mul_f32_e32 v87, v28, v87
	v_mul_f32_e32 v84, v84, v52
	v_mul_f32_e32 v85, v85, v53
	v_mul_f32_e32 v86, v86, v54
	v_mul_f32_e32 v87, v87, v55
	global_store_dwordx4 v[14:15], v[84:87], off offset:1024
	v_mul_f32_e32 v88, v28, v88
	v_mul_f32_e32 v89, v28, v89
	v_mul_f32_e32 v90, v28, v90
	v_mul_f32_e32 v91, v28, v91
	v_mul_f32_e32 v88, v88, v56
	v_mul_f32_e32 v89, v89, v57
	v_mul_f32_e32 v90, v90, v58
	v_mul_f32_e32 v91, v91, v59
	global_store_dwordx4 v[14:15], v[88:91], off offset:2048
	v_mul_f32_e32 v92, v28, v92
	v_mul_f32_e32 v93, v28, v93
	v_mul_f32_e32 v94, v28, v94
	v_mul_f32_e32 v95, v28, v95
	v_mul_f32_e32 v92, v92, v60
	v_mul_f32_e32 v93, v93, v61
	v_mul_f32_e32 v94, v94, v62
	v_mul_f32_e32 v95, v95, v63
	global_store_dwordx4 v[14:15], v[92:95], off offset:3072
	s_branch .Lp8_loop
; #define KIN(i) (*(const float* const __attribute__((address_space(4)))*)(kp + 8 * (i)))
; __global__ void __launch_bounds__(NTHREADS, 2) fwd_megakernel(Args args) {
;     ...
;         const float* ss3 = SS + 3 * T; const f32x4* gf = (const f32x4*)KIN(19);
;         f32x4* X4 = (f32x4*)X;
;         for (int row = gw; row < T; row += NGW) {
;             f32x4* xr = X4 + (size_t)row * (D / 4) + lane;
;             const float r = __builtin_amdgcn_rsqf(ss3[row] * (1.0f / D) + EPS);
;             f32x4 v[8];
; #pragma unroll
;             for (int j = 0; j < 8; ++j) v[j] = xr[64 * j];
; #pragma unroll
;             for (int j = 0; j < 8; ++j) xr[64 * j] = v[j] * r * gf[lane + 64 * j];
;         }
.Lp8_tail_a:
	s_waitcnt vmcnt(0)
	v_fmamk_f32 v28, v28, 0x3a000000, v0
	v_rsq_f32_e32 v28, v28
	s_nop 0
	v_mul_f32_e32 v64, v28, v64
	v_mul_f32_e32 v65, v28, v65
	v_mul_f32_e32 v66, v28, v66
	v_mul_f32_e32 v67, v28, v67
	v_mul_f32_e32 v64, v64, v32
	v_mul_f32_e32 v65, v65, v33
	v_mul_f32_e32 v66, v66, v34
	v_mul_f32_e32 v67, v67, v35
	global_store_dwordx4 v[14:15], v[64:67], off offset:-4096
	v_mul_f32_e32 v68, v28, v68
	v_mul_f32_e32 v69, v28, v69
	v_mul_f32_e32 v70, v28, v70
	v_mul_f32_e32 v71, v28, v71
	v_mul_f32_e32 v68, v68, v36
	v_mul_f32_e32 v69, v69, v37
	v_mul_f32_e32 v70, v70, v38
	v_mul_f32_e32 v71, v71, v39
	global_store_dwordx4 v[14:15], v[68:71], off offset:-3072
	v_mul_f32_e32 v72, v28, v72
	v_mul_f32_e32 v73, v28, v73
	v_mul_f32_e32 v74, v28, v74
	v_mul_f32_e32 v75, v28, v75
	v_mul_f32_e32 v72, v72, v40
	v_mul_f32_e32 v73, v73, v41
	v_mul_f32_e32 v74, v74, v42
	v_mul_f32_e32 v75, v75, v43
	global_store_dwordx4 v[14:15], v[72:75], off offset:-2048
	v_mul_f32_e32 v76, v28, v76
	v_mul_f32_e32 v77, v28, v77
	v_mul_f32_e32 v78, v28, v78
	v_mul_f32_e32 v79, v28, v79
	v_mul_f32_e32 v76, v76, v44
	v_mul_f32_e32 v77, v77, v45
	v_mul_f32_e32 v78, v78, v46
	v_mul_f32_e32 v79, v79, v47
	global_store_dwordx4 v[14:15], v[76:79], off offset:-1024
	v_mul_f32_e32 v80, v28, v80
	v_mul_f32_e32 v81, v28, v81
	v_mul_f32_e32 v82, v28, v82
	v_mul_f32_e32 v83, v28, v83
	v_mul_f32_e32 v80, v80, v48
	v_mul_f32_e32 v81, v81, v49
	v_mul_f32_e32 v82, v82, v50
	v_mul_f32_e32 v83, v83, v51
	global_store_dwordx4 v[14:15], v[80:83], off offset:0
	v_mul_f32_e32 v84, v28, v84
	v_mul_f32_e32 v85, v28, v85
	v_mul_f32_e32 v86, v28, v86
	v_mul_f32_e32 v87, v28, v87
	v_mul_f32_e32 v84, v84, v52
	v_mul_f32_e32 v85, v85, v53
	v_mul_f32_e32 v86, v86, v54
	v_mul_f32_e32 v87, v87, v55
	global_store_dwordx4 v[14:15], v[84:87], off offset:1024
	v_mul_f32_e32 v88, v28, v88
	v_mul_f32_e32 v89, v28, v89
	v_mul_f32_e32 v90, v28, v90
	v_mul_f32_e32 v91, v28, v91
	v_mul_f32_e32 v88, v88, v56
	v_mul_f32_e32 v89, v89, v57
	v_mul_f32_e32 v90, v90, v58
	v_mul_f32_e32 v91, v91, v59
	global_store_dwordx4 v[14:15], v[88:91], off offset:2048
	v_mul_f32_e32 v92, v28, v92
	v_mul_f32_e32 v93, v28, v93
	v_mul_f32_e32 v94, v28, v94
	v_mul_f32_e32 v95, v28, v95
	v_mul_f32_e32 v92, v92, v60
	v_mul_f32_e32 v93, v93, v61
	v_mul_f32_e32 v94, v94, v62
	v_mul_f32_e32 v95, v95, v63
	global_store_dwordx4 v[14:15], v[92:95], off offset:3072
	s_endpgm
.Lp8_tail_b:
	s_waitcnt vmcnt(0)
	v_fmamk_f32 v30, v30, 0x3a000000, v0
	v_rsq_f32_e32 v30, v30
	s_nop 0
	v_mul_f32_e32 v96, v30, v96
	v_mul_f32_e32 v97, v30, v97
	v_mul_f32_e32 v98, v30, v98
	v_mul_f32_e32 v99, v30, v99
	v_mul_f32_e32 v96, v96, v32
	v_mul_f32_e32 v97, v97, v33
	v_mul_f32_e32 v98, v98, v34
	v_mul_f32_e32 v99, v99, v35
	global_store_dwordx4 v[16:17], v[96:99], off offset:-4096
	v_mul_f32_e32 v100, v30, v100
	v_mul_f32_e32 v101, v30, v101
	v_mul_f32_e32 v102, v30, v102
	v_mul_f32_e32 v103, v30, v103
	v_mul_f32_e32 v100, v100, v36
	v_mul_f32_e32 v101, v101, v37
	v_mul_f32_e32 v102, v102, v38
	v_mul_f32_e32 v103, v103, v39
	global_store_dwordx4 v[16:17], v[100:103], off offset:-3072
	v_mul_f32_e32 v104, v30, v104
	v_mul_f32_e32 v105, v30, v105
	v_mul_f32_e32 v106, v30, v106
	v_mul_f32_e32 v107, v30, v107
	v_mul_f32_e32 v104, v104, v40
	v_mul_f32_e32 v105, v105, v41
	v_mul_f32_e32 v106, v106, v42
	v_mul_f32_e32 v107, v107, v43
	global_store_dwordx4 v[16:17], v[104:107], off offset:-2048
	v_mul_f32_e32 v108, v30, v108
	v_mul_f32_e32 v109, v30, v109
	v_mul_f32_e32 v110, v30, v110
	v_mul_f32_e32 v111, v30, v111
	v_mul_f32_e32 v108, v108, v44
	v_mul_f32_e32 v109, v109, v45
	v_mul_f32_e32 v110, v110, v46
	v_mul_f32_e32 v111, v111, v47
	global_store_dwordx4 v[16:17], v[108:111], off offset:-1024
	v_mul_f32_e32 v112, v30, v112
	v_mul_f32_e32 v113, v30, v113
	v_mul_f32_e32 v114, v30, v114
	v_mul_f32_e32 v115, v30, v115
	v_mul_f32_e32 v112, v112, v48
	v_mul_f32_e32 v113, v113, v49
	v_mul_f32_e32 v114, v114, v50
	v_mul_f32_e32 v115, v115, v51
	global_store_dwordx4 v[16:17], v[112:115], off offset:0
	v_mul_f32_e32 v116, v30, v116
	v_mul_f32_e32 v117, v30, v117
	v_mul_f32_e32 v118, v30, v118
	v_mul_f32_e32 v119, v30, v119
	v_mul_f32_e32 v116, v116, v52
	v_mul_f32_e32 v117, v117, v53
	v_mul_f32_e32 v118, v118, v54
	v_mul_f32_e32 v119, v119, v55
	global_store_dwordx4 v[16:17], v[116:119], off offset:1024
	v_mul_f32_e32 v120, v30, v120
	v_mul_f32_e32 v121, v30, v121
	v_mul_f32_e32 v122, v30, v122
	v_mul_f32_e32 v123, v30, v123
	v_mul_f32_e32 v120, v120, v56
	v_mul_f32_e32 v121, v121, v57
	v_mul_f32_e32 v122, v122, v58
	v_mul_f32_e32 v123, v123, v59
	global_store_dwordx4 v[16:17], v[120:123], off offset:2048
	v_mul_f32_e32 v124, v30, v124
	v_mul_f32_e32 v125, v30, v125
	v_mul_f32_e32 v126, v30, v126
	v_mul_f32_e32 v127, v30, v127
	v_mul_f32_e32 v124, v124, v60
	v_mul_f32_e32 v125, v125, v61
	v_mul_f32_e32 v126, v126, v62
	v_mul_f32_e32 v127, v127, v63
	global_store_dwordx4 v[16:17], v[124:127], off offset:3072
